# v15
# speedup vs baseline: 1.0075x; 1.0075x over previous
; __device__ __forceinline__ void partialSM(f32x16& p0, f32x16& p1, float& m_reg, float& mn, float& alpha) {
;     float pmax = p0[0]; for (int r = 1; r < 16; ++r) pmax = fmaxf(pmax, p0[r]); for (int r = 0; r < 16; ++r) pmax = fmaxf(pmax, p1[r]);
;     { auto rr = __builtin_amdgcn_permlane32_swap(__float_as_uint(pmax), __float_as_uint(pmax), false, false);
;       pmax = fmaxf(__uint_as_float(rr[0]), __uint_as_float(rr[1])); }
;     constexpr float C2 = 1.4426950408889634f * SCALE;
;     if (__builtin_expect(__all((pmax - m_reg) * SCALE <= THR), 1)) { mn = m_reg; alpha = 1.f; }
;     else { mn = fmaxf(m_reg, pmax); alpha = __builtin_amdgcn_exp2f((m_reg - mn) * C2); m_reg = mn; }
;     const float mnL = -mn * C2;
;     for (int r = 0; r < 16; ++r) p0[r] = fmaf(p0[r], C2, mnL); for (int r = 0; r < 16; ++r) p1[r] = fmaf(p1[r], C2, mnL);
;     for (int r = 0; r < 16; ++r) p0[r] = __builtin_amdgcn_exp2f(p0[r]);
; }
; template <int VB, bool SK>
; __device__ __forceinline__ void pv_tile(f32x16* o, int vb0, bf16x8 pa0, bf16x8 pa1, bf16x8 pa2, bf16x8 pa3, bool act) {
;     if (SK && !act) return;
;     ...
;     PV_D0(0); PV_D0(1); PV_D0(2); PV_D0(3);
.Lmy_h1_pv:
	ds_read_b64_tr_b16 v[224:225], v173 offset:0
	ds_read_b64_tr_b16 v[226:227], v173 offset:2048
	ds_read_b64_tr_b16 v[240:241], v173 offset:512
	ds_read_b64_tr_b16 v[242:243], v173 offset:2560
	ds_read_b64_tr_b16 v[244:245], v173 offset:1024
	ds_read_b64_tr_b16 v[246:247], v173 offset:3072
	ds_read_b64_tr_b16 v[248:249], v173 offset:1536
	ds_read_b64_tr_b16 v[250:251], v173 offset:3584
	v_max_f32_e32 v239, v81, v81
	v_max_f32_e32 v252, v80, v80
	v_max_f32_e32 v239, v252, v239
	s_waitcnt lgkmcnt(6)
	v_mfma_f32_32x32x16_bf16 v[32:47], v[144:147], v[224:227], v[32:47]
	v_max3_f32 v239, v239, v82, v83
	v_max3_f32 v239, v239, v84, v85
	ds_read_b64_tr_b16 v[224:225], v173 offset:4096
	ds_read_b64_tr_b16 v[226:227], v173 offset:6144
	v_max3_f32 v239, v239, v86, v87
	v_max3_f32 v239, v239, v88, v89
	v_max3_f32 v239, v239, v90, v91
	s_waitcnt lgkmcnt(6)
	v_mfma_f32_32x32x16_bf16 v[48:63], v[144:147], v[240:243], v[48:63]
	v_max3_f32 v239, v239, v92, v93
	v_max3_f32 v239, v239, v94, v95
	ds_read_b64_tr_b16 v[240:241], v173 offset:4608
	ds_read_b64_tr_b16 v[242:243], v173 offset:6656
	v_max3_f32 v239, v239, v64, v65
	v_max3_f32 v239, v239, v66, v67
	v_max3_f32 v239, v239, v68, v69
	s_waitcnt lgkmcnt(6)
	v_mfma_f32_32x32x16_bf16 v[16:31], v[144:147], v[244:247], v[16:31]
	v_max3_f32 v239, v239, v70, v71
	v_max3_f32 v239, v239, v72, v73
	ds_read_b64_tr_b16 v[244:245], v173 offset:5120
	ds_read_b64_tr_b16 v[246:247], v173 offset:7168
	v_max3_f32 v239, v239, v74, v75
	v_max3_f32 v239, v239, v76, v77
	v_max3_f32 v239, v239, v78, v79
	s_waitcnt lgkmcnt(6)
	v_mfma_f32_32x32x16_bf16 v[0:15], v[144:147], v[248:251], v[0:15]
	v_mov_b32_e32 v252, v239
	s_nop 1
	ds_read_b64_tr_b16 v[248:249], v173 offset:5632
	ds_read_b64_tr_b16 v[250:251], v173 offset:7680
	v_permlane32_swap_b32_e32 v239, v252
	v_max_f32_e32 v252, v252, v252
	v_max_f32_e32 v239, v239, v239
	s_waitcnt lgkmcnt(6)
	v_mfma_f32_32x32x16_bf16 v[32:47], v[148:151], v[224:227], v[32:47]
	v_max_f32_e32 v239, v239, v252
	v_sub_f32_e32 v252, v239, v184
	ds_read_b64_tr_b16 v[224:225], v173 offset:8192
	ds_read_b64_tr_b16 v[226:227], v173 offset:10240
	v_mul_f32_e32 v252, 0x3db504f3, v252
	v_cmp_ge_f32_e32 vcc, s66, v252
	v_max_f32_e32 v252, v184, v184
	s_waitcnt lgkmcnt(6)
	v_mfma_f32_32x32x16_bf16 v[48:63], v[148:151], v[240:243], v[48:63]
	v_max_f32_e32 v239, v252, v239
	v_sub_f32_e32 v252, v184, v239
	ds_read_b64_tr_b16 v[240:241], v173 offset:8704
	ds_read_b64_tr_b16 v[242:243], v173 offset:10752
	v_mul_f32_e32 v252, 0x3e0293ee, v252
	v_exp_f32_e32 v252, v252
	s_cmp_eq_u64 vcc, exec
	s_waitcnt lgkmcnt(6)
	v_mfma_f32_32x32x16_bf16 v[16:31], v[148:151], v[244:247], v[16:31]
	s_cselect_b64 s[42:43], -1, 0
	v_cndmask_b32_e64 v184, v239, v184, s[42:43]
	ds_read_b64_tr_b16 v[244:245], v173 offset:9216
	ds_read_b64_tr_b16 v[246:247], v173 offset:11264
	v_mul_f32_e32 v228, 0xbe0293ee, v184
	v_fmamk_f32 v80, v80, 0x3e0293ee, v228
	v_fmamk_f32 v81, v81, 0x3e0293ee, v228
	s_waitcnt lgkmcnt(6)
	v_mfma_f32_32x32x16_bf16 v[0:15], v[148:151], v[248:251], v[0:15]
	v_fmamk_f32 v82, v82, 0x3e0293ee, v228
	v_fmamk_f32 v83, v83, 0x3e0293ee, v228
	ds_read_b64_tr_b16 v[248:249], v173 offset:9728
	ds_read_b64_tr_b16 v[250:251], v173 offset:11776
	v_fmamk_f32 v84, v84, 0x3e0293ee, v228
	v_fmamk_f32 v85, v85, 0x3e0293ee, v228
	v_fmamk_f32 v86, v86, 0x3e0293ee, v228
	s_waitcnt lgkmcnt(6)
	v_mfma_f32_32x32x16_bf16 v[32:47], v[152:155], v[224:227], v[32:47]
	v_fmamk_f32 v87, v87, 0x3e0293ee, v228
	v_fmamk_f32 v88, v88, 0x3e0293ee, v228
	ds_read_b64_tr_b16 v[224:225], v173 offset:12288
	ds_read_b64_tr_b16 v[226:227], v173 offset:14336
	v_fmamk_f32 v89, v89, 0x3e0293ee, v228
	v_fmamk_f32 v90, v90, 0x3e0293ee, v228
	v_fmamk_f32 v91, v91, 0x3e0293ee, v228
	s_waitcnt lgkmcnt(6)
	v_mfma_f32_32x32x16_bf16 v[48:63], v[152:155], v[240:243], v[48:63]
	v_fmamk_f32 v92, v92, 0x3e0293ee, v228
	v_fmamk_f32 v93, v93, 0x3e0293ee, v228
	ds_read_b64_tr_b16 v[240:241], v173 offset:12800
	ds_read_b64_tr_b16 v[242:243], v173 offset:14848
	v_fmamk_f32 v94, v94, 0x3e0293ee, v228
	v_fmamk_f32 v95, v95, 0x3e0293ee, v228
	v_exp_f32_e32 v144, v80
	s_waitcnt lgkmcnt(6)
	v_mfma_f32_32x32x16_bf16 v[16:31], v[152:155], v[244:247], v[16:31]
	v_exp_f32_e32 v145, v81
	v_exp_f32_e32 v146, v82
	ds_read_b64_tr_b16 v[244:245], v173 offset:13312
	ds_read_b64_tr_b16 v[246:247], v173 offset:15360
	v_exp_f32_e32 v147, v86
	v_fmamk_f32 v199, v64, 0x3e0293ee, v228
	v_fmamk_f32 v210, v65, 0x3e0293ee, v228
	s_waitcnt lgkmcnt(6)
	v_mfma_f32_32x32x16_bf16 v[0:15], v[152:155], v[248:251], v[0:15]
	v_fmamk_f32 v211, v66, 0x3e0293ee, v228
	v_fmamk_f32 v212, v67, 0x3e0293ee, v228
	ds_read_b64_tr_b16 v[248:249], v173 offset:13824
	ds_read_b64_tr_b16 v[250:251], v173 offset:15872
	v_exp_f32_e32 v148, v88
	v_exp_f32_e32 v149, v89
	v_exp_f32_e32 v150, v92
	s_waitcnt lgkmcnt(6)
	v_mfma_f32_32x32x16_bf16 v[32:47], v[156:159], v[224:227], v[32:47]
	v_exp_f32_e32 v151, v93
	v_fmamk_f32 v213, v68, 0x3e0293ee, v228
	v_fmamk_f32 v192, v69, 0x3e0293ee, v228
	v_fmamk_f32 v193, v70, 0x3e0293ee, v228
	v_fmamk_f32 v194, v71, 0x3e0293ee, v228
	s_waitcnt lgkmcnt(4)
	v_mfma_f32_32x32x16_bf16 v[48:63], v[156:159], v[240:243], v[48:63]
	v_fmamk_f32 v195, v72, 0x3e0293ee, v228
	v_fmamk_f32 v196, v73, 0x3e0293ee, v228
	v_exp_f32_e32 v152, v94
	v_exp_f32_e32 v153, v95
	v_exp_f32_e32 v154, v90
	s_waitcnt lgkmcnt(2)
	v_mfma_f32_32x32x16_bf16 v[16:31], v[156:159], v[244:247], v[16:31]
	v_exp_f32_e32 v155, v91
	v_fmamk_f32 v197, v74, 0x3e0293ee, v228
	v_fmamk_f32 v198, v75, 0x3e0293ee, v228
	v_fmamk_f32 v191, v76, 0x3e0293ee, v228
	v_fmamk_f32 v214, v77, 0x3e0293ee, v228
	s_waitcnt lgkmcnt(0)
	v_mfma_f32_32x32x16_bf16 v[0:15], v[156:159], v[248:251], v[0:15]
	v_fmamk_f32 v215, v78, 0x3e0293ee, v228
	v_fmamk_f32 v190, v79, 0x3e0293ee, v228
	v_exp_f32_e32 v156, v87
	v_exp_f32_e32 v157, v83
	v_exp_f32_e32 v158, v84
	v_exp_f32_e32 v159, v85
	s_waitcnt vmcnt(0)
	ds_write_b128 v176, v[136:139] offset:32768
	ds_write_b128 v176, v[140:143] offset:40960
	s_waitcnt lgkmcnt(0)
	s_barrier
	v_cndmask_b32_e64 v189, v252, 1.0, s[42:43]
	v_cmp_gt_f32_e32 vcc, 1.0, v189
	ds_write_b128 v181, v[128:131]
	ds_write_b128 v182, v[132:135]
	s_cbranch_vccz .LBB0_211
	s_and_saveexec_b64 s[8:9], s[40:41]
	ds_write_b32 v175, v189 offset:128
	s_or_b64 exec, exec, s[8:9]
	s_waitcnt lgkmcnt(0)
	ds_read_b128 v[128:131], v174 offset:224
	ds_read_b128 v[132:135], v174 offset:192
	ds_read_b128 v[136:139], v174 offset:160
	ds_read_b128 v[140:143], v174 offset:128
	s_waitcnt lgkmcnt(3)
	v_pk_mul_f32 v[46:47], v[46:47], v[130:131]
	s_waitcnt lgkmcnt(2)
	v_pk_mul_f32 v[42:43], v[42:43], v[134:135]
	s_waitcnt lgkmcnt(1)
	v_pk_mul_f32 v[38:39], v[38:39], v[138:139]
	s_waitcnt lgkmcnt(0)
	v_pk_mul_f32 v[34:35], v[34:35], v[142:143]
	v_pk_mul_f32 v[44:45], v[44:45], v[128:129]
	v_pk_mul_f32 v[40:41], v[40:41], v[132:133]
	v_pk_mul_f32 v[36:37], v[36:37], v[136:137]
	v_pk_mul_f32 v[32:33], v[32:33], v[140:141]
	v_pk_mul_f32 v[62:63], v[62:63], v[130:131]
	v_pk_mul_f32 v[58:59], v[58:59], v[134:135]
	v_pk_mul_f32 v[54:55], v[54:55], v[138:139]
	v_pk_mul_f32 v[50:51], v[50:51], v[142:143]
	v_pk_mul_f32 v[60:61], v[60:61], v[128:129]
	v_pk_mul_f32 v[56:57], v[56:57], v[132:133]
	v_pk_mul_f32 v[52:53], v[52:53], v[136:137]
	v_pk_mul_f32 v[48:49], v[48:49], v[140:141]
	v_pk_mul_f32 v[30:31], v[30:31], v[130:131]
	v_pk_mul_f32 v[26:27], v[26:27], v[134:135]
	v_pk_mul_f32 v[22:23], v[22:23], v[138:139]
	v_pk_mul_f32 v[18:19], v[18:19], v[142:143]
	v_pk_mul_f32 v[28:29], v[28:29], v[128:129]
	v_pk_mul_f32 v[24:25], v[24:25], v[132:133]
	v_pk_mul_f32 v[20:21], v[20:21], v[136:137]
	v_pk_mul_f32 v[16:17], v[16:17], v[140:141]
	v_pk_mul_f32 v[14:15], v[14:15], v[130:131]
	v_pk_mul_f32 v[10:11], v[10:11], v[134:135]
	v_pk_mul_f32 v[6:7], v[6:7], v[138:139]
	v_pk_mul_f32 v[2:3], v[2:3], v[142:143]
	v_pk_mul_f32 v[12:13], v[12:13], v[128:129]
	v_pk_mul_f32 v[8:9], v[8:9], v[132:133]
	v_pk_mul_f32 v[4:5], v[4:5], v[136:137]
	v_pk_mul_f32 v[0:1], v[0:1], v[140:141]
.LBB0_211:
	s_waitcnt lgkmcnt(0)
	s_add_i32 s42, s73, 1
	s_cmp_lt_u32 s42, s71
	s_cselect_b64 s[8:9], -1, 0
	s_cmp_ge_u32 s42, s71
	s_cbranch_scc1 .Lmy_h2_ld
	v_add_u32_e32 v128, 0x41, v188
	v_add_u32_e32 v130, 0x61, v188
	v_ashrrev_i32_e32 v129, 31, v128
	v_ashrrev_i32_e32 v131, 31, v130
	v_lshlrev_b64 v[136:137], 8, v[128:129]
	v_lshlrev_b64 v[138:139], 8, v[130:131]
	v_lshl_add_u64 v[128:129], v[166:167], 0, v[136:137]
	v_lshl_add_u64 v[132:133], v[166:167], 0, v[138:139]
	v_lshl_add_u64 v[136:137], v[168:169], 0, v[136:137]
	v_lshl_add_u64 v[140:141], v[168:169], 0, v[138:139]
	global_load_dwordx4 v[128:131], v[128:129], off
	s_nop 0
	global_load_dwordx4 v[132:135], v[132:133], off
	s_nop 0
	global_load_dwordx4 v[136:139], v[136:137], off
	s_nop 0
	global_load_dwordx4 v[140:143], v[140:141], off

; __device__ __forceinline__ void partialSM(f32x16& p0, f32x16& p1, float& m_reg, float& mn, float& alpha) {
;     float pmax = p0[0]; for (int r = 1; r < 16; ++r) pmax = fmaxf(pmax, p0[r]); for (int r = 0; r < 16; ++r) pmax = fmaxf(pmax, p1[r]);
;     { auto rr = __builtin_amdgcn_permlane32_swap(__float_as_uint(pmax), __float_as_uint(pmax), false, false);
;       pmax = fmaxf(__uint_as_float(rr[0]), __uint_as_float(rr[1])); }
;     constexpr float C2 = 1.4426950408889634f * SCALE;
;     if (__builtin_expect(__all((pmax - m_reg) * SCALE <= THR), 1)) { mn = m_reg; alpha = 1.f; }
;     else { mn = fmaxf(m_reg, pmax); alpha = __builtin_amdgcn_exp2f((m_reg - mn) * C2); m_reg = mn; }
;     const float mnL = -mn * C2;
;     for (int r = 0; r < 16; ++r) p0[r] = fmaf(p0[r], C2, mnL); for (int r = 0; r < 16; ++r) p1[r] = fmaf(p1[r], C2, mnL);
;     for (int r = 0; r < 16; ++r) p0[r] = __builtin_amdgcn_exp2f(p0[r]);
; }
; template <int VB, bool SK>
; __device__ __forceinline__ void pv_tile(f32x16* o, int vb0, bf16x8 pa0, bf16x8 pa1, bf16x8 pa2, bf16x8 pa3, bool act) {
;     if (SK && !act) return;
;     ...
;     PV_D0(0); PV_D0(1); PV_D0(2); PV_D0(3);
.Lmy_h2_pv:
	ds_read_b64_tr_b16 v[224:225], v173 offset:16384
	ds_read_b64_tr_b16 v[226:227], v173 offset:18432
	ds_read_b64_tr_b16 v[240:241], v173 offset:16896
	ds_read_b64_tr_b16 v[242:243], v173 offset:18944
	ds_read_b64_tr_b16 v[244:245], v173 offset:17408
	ds_read_b64_tr_b16 v[246:247], v173 offset:19456
	ds_read_b64_tr_b16 v[248:249], v173 offset:17920
	ds_read_b64_tr_b16 v[250:251], v173 offset:19968
	v_max_f32_e32 v239, v81, v81
	v_max_f32_e32 v252, v80, v80
	v_max_f32_e32 v239, v252, v239
	s_waitcnt lgkmcnt(6)
	v_mfma_f32_32x32x16_bf16 v[32:47], v[144:147], v[224:227], v[32:47]
	v_max3_f32 v239, v239, v82, v83
	v_max3_f32 v239, v239, v84, v85
	ds_read_b64_tr_b16 v[224:225], v173 offset:20480
	ds_read_b64_tr_b16 v[226:227], v173 offset:22528
	v_max3_f32 v239, v239, v86, v87
	v_max3_f32 v239, v239, v88, v89
	v_max3_f32 v239, v239, v90, v91
	s_waitcnt lgkmcnt(6)
	v_mfma_f32_32x32x16_bf16 v[48:63], v[144:147], v[240:243], v[48:63]
	v_max3_f32 v239, v239, v92, v93
	v_max3_f32 v239, v239, v94, v95
	ds_read_b64_tr_b16 v[240:241], v173 offset:20992
	ds_read_b64_tr_b16 v[242:243], v173 offset:23040
	v_max3_f32 v239, v239, v64, v65
	v_max3_f32 v239, v239, v66, v67
	v_max3_f32 v239, v239, v68, v69
	s_waitcnt lgkmcnt(6)
	v_mfma_f32_32x32x16_bf16 v[16:31], v[144:147], v[244:247], v[16:31]
	v_max3_f32 v239, v239, v70, v71
	v_max3_f32 v239, v239, v72, v73
	ds_read_b64_tr_b16 v[244:245], v173 offset:21504
	ds_read_b64_tr_b16 v[246:247], v173 offset:23552
	v_max3_f32 v239, v239, v74, v75
	v_max3_f32 v239, v239, v76, v77
	v_max3_f32 v239, v239, v78, v79
	s_waitcnt lgkmcnt(6)
	v_mfma_f32_32x32x16_bf16 v[0:15], v[144:147], v[248:251], v[0:15]
	v_mov_b32_e32 v252, v239
	s_nop 1
	ds_read_b64_tr_b16 v[248:249], v173 offset:22016
	ds_read_b64_tr_b16 v[250:251], v173 offset:24064
	v_permlane32_swap_b32_e32 v239, v252
	v_max_f32_e32 v252, v252, v252
	v_max_f32_e32 v239, v239, v239
	s_waitcnt lgkmcnt(6)
	v_mfma_f32_32x32x16_bf16 v[32:47], v[148:151], v[224:227], v[32:47]
	v_max_f32_e32 v239, v239, v252
	v_sub_f32_e32 v252, v239, v184
	ds_read_b64_tr_b16 v[224:225], v173 offset:24576
	ds_read_b64_tr_b16 v[226:227], v173 offset:26624
	v_mul_f32_e32 v252, 0x3db504f3, v252
	v_cmp_ge_f32_e32 vcc, s66, v252
	s_cmp_eq_u64 vcc, exec
	s_waitcnt lgkmcnt(6)
	v_mfma_f32_32x32x16_bf16 v[48:63], v[148:151], v[240:243], v[48:63]
	s_cselect_b64 s[42:43], -1, 0
	v_max_f32_e32 v253, v184, v184
	ds_read_b64_tr_b16 v[240:241], v173 offset:25088
	ds_read_b64_tr_b16 v[242:243], v173 offset:27136
	v_max_f32_e32 v253, v253, v239
	v_sub_f32_e32 v252, v184, v253
	v_mul_f32_e32 v252, 0x3e0293ee, v252
	s_waitcnt lgkmcnt(6)
	v_mfma_f32_32x32x16_bf16 v[16:31], v[148:151], v[244:247], v[16:31]
	v_exp_f32_e32 v252, v252
	s_nop 0
	ds_read_b64_tr_b16 v[244:245], v173 offset:25600
	ds_read_b64_tr_b16 v[246:247], v173 offset:27648
	v_cndmask_b32_e64 v188, v252, 1.0, s[42:43]
	v_cndmask_b32_e64 v184, v253, v184, s[42:43]
	v_mul_f32_e32 v228, 0xbe0293ee, v184
	s_waitcnt lgkmcnt(6)
	v_mfma_f32_32x32x16_bf16 v[0:15], v[148:151], v[248:251], v[0:15]
	v_mov_b32_e32 v229, v228
	v_fmamk_f32 v80, v80, 0x3e0293ee, v228
	ds_read_b64_tr_b16 v[248:249], v173 offset:26112
	ds_read_b64_tr_b16 v[250:251], v173 offset:28160
	v_fmamk_f32 v81, v81, 0x3e0293ee, v228
	v_fmamk_f32 v82, v82, 0x3e0293ee, v228
	v_fmamk_f32 v83, v83, 0x3e0293ee, v228
	s_waitcnt lgkmcnt(6)
	v_mfma_f32_32x32x16_bf16 v[32:47], v[152:155], v[224:227], v[32:47]
	v_fmamk_f32 v84, v84, 0x3e0293ee, v228
	v_fmamk_f32 v85, v85, 0x3e0293ee, v228
	ds_read_b64_tr_b16 v[224:225], v173 offset:28672
	ds_read_b64_tr_b16 v[226:227], v173 offset:30720
	v_fmamk_f32 v86, v86, 0x3e0293ee, v228
	v_fmamk_f32 v87, v87, 0x3e0293ee, v228
	v_fmamk_f32 v88, v88, 0x3e0293ee, v228
	s_waitcnt lgkmcnt(6)
	v_mfma_f32_32x32x16_bf16 v[48:63], v[152:155], v[240:243], v[48:63]
	v_fmamk_f32 v89, v89, 0x3e0293ee, v228
	v_fmamk_f32 v90, v90, 0x3e0293ee, v228
	ds_read_b64_tr_b16 v[240:241], v173 offset:29184
	ds_read_b64_tr_b16 v[242:243], v173 offset:31232
	v_fmamk_f32 v91, v91, 0x3e0293ee, v228
	v_fmamk_f32 v92, v92, 0x3e0293ee, v228
	v_fmamk_f32 v93, v93, 0x3e0293ee, v228
	s_waitcnt lgkmcnt(6)
	v_mfma_f32_32x32x16_bf16 v[16:31], v[152:155], v[244:247], v[16:31]
	v_fmamk_f32 v94, v94, 0x3e0293ee, v228
	v_fmac_f32_e32 v229, 0x3e0293ee, v95
	ds_read_b64_tr_b16 v[244:245], v173 offset:29696
	ds_read_b64_tr_b16 v[246:247], v173 offset:31744
	v_exp_f32_e32 v198, v80
	v_exp_f32_e32 v199, v81
	v_exp_f32_e32 v210, v82
	s_waitcnt lgkmcnt(6)
	v_mfma_f32_32x32x16_bf16 v[0:15], v[152:155], v[248:251], v[0:15]
	v_exp_f32_e32 v212, v83
	v_exp_f32_e32 v213, v84
	ds_read_b64_tr_b16 v[248:249], v173 offset:30208
	ds_read_b64_tr_b16 v[250:251], v173 offset:32256
	v_exp_f32_e32 v215, v85
	v_exp_f32_e32 v211, v86
	v_exp_f32_e32 v214, v87
	s_waitcnt lgkmcnt(6)
	v_mfma_f32_32x32x16_bf16 v[32:47], v[156:159], v[224:227], v[32:47]
	v_exp_f32_e32 v190, v88
	v_exp_f32_e32 v192, v89
	v_exp_f32_e32 v193, v90
	v_exp_f32_e32 v196, v91
	v_exp_f32_e32 v191, v92
	s_waitcnt lgkmcnt(4)
	v_mfma_f32_32x32x16_bf16 v[48:63], v[156:159], v[240:243], v[48:63]
	v_exp_f32_e32 v194, v93
	v_exp_f32_e32 v195, v94
	v_exp_f32_e32 v197, v229
	v_fmamk_f32 v144, v72, 0x3e0293ee, v228
	v_fmamk_f32 v145, v73, 0x3e0293ee, v228
	s_waitcnt lgkmcnt(2)
	v_mfma_f32_32x32x16_bf16 v[16:31], v[156:159], v[244:247], v[16:31]
	v_fmamk_f32 v146, v78, 0x3e0293ee, v228
	v_fmamk_f32 v147, v79, 0x3e0293ee, v228
	v_fmamk_f32 v148, v70, 0x3e0293ee, v228
	v_fmamk_f32 v149, v71, 0x3e0293ee, v228
	v_fmamk_f32 v150, v68, 0x3e0293ee, v228
	s_waitcnt lgkmcnt(0)
	v_mfma_f32_32x32x16_bf16 v[0:15], v[156:159], v[248:251], v[0:15]
	v_fmamk_f32 v151, v69, 0x3e0293ee, v228
	v_fmamk_f32 v152, v76, 0x3e0293ee, v228
	v_fmamk_f32 v153, v77, 0x3e0293ee, v228
	v_fmamk_f32 v154, v66, 0x3e0293ee, v228
	v_fmamk_f32 v155, v67, 0x3e0293ee, v228
	v_fmamk_f32 v156, v64, 0x3e0293ee, v228
	v_fmamk_f32 v157, v65, 0x3e0293ee, v228
	v_fmamk_f32 v158, v74, 0x3e0293ee, v228
	v_fmamk_f32 v159, v75, 0x3e0293ee, v228
	s_andn2_b64 vcc, exec, s[8:9]
	s_cbranch_vccnz .Lmy_h2_skipk
	s_waitcnt vmcnt(0)
	ds_write_b128 v176, v[136:139] offset:49152
	ds_write_b128 v176, v[140:143] offset:57344
; template <class TIn, class TOut>
; __device__ __forceinline__ void causal_swa_block(const BlockRef<TIn, TOut>& cur, const BlockRef<TIn, TOut>& nxt, int skv, int W, char* lds, Seam<TIn>& S) {
;     ...
;     for (int t = 1; t + 1 < NT; t += 2) {
;         HALF_STEP(pB0, pB1, mnB, alB, pA0, pA1, alA, t, 1, 0, 0);
;         HALF_STEP(pA0, pA1, mnA, alA, pB0, pB1, alB, t + 1, 0, 1, 1);
;     }
.Lmy_h2_skipk:
	s_waitcnt lgkmcnt(0)
	s_barrier
	s_andn2_b64 vcc, exec, s[8:9]
	s_cbranch_vccnz .LBB0_217
	ds_write_b128 v181, v[128:131] offset:16384
	ds_write_b128 v182, v[132:135] offset:16384
.LBB0_217:
	v_cmp_gt_f32_e32 vcc, 1.0, v188
	s_cbranch_vccz .LBB0_221
	s_and_saveexec_b64 s[8:9], s[40:41]
	ds_write_b32 v175, v188 offset:128
	s_or_b64 exec, exec, s[8:9]
	s_waitcnt lgkmcnt(0)
	s_waitcnt vmcnt(2)
	ds_read_b128 v[128:131], v174 offset:224
	s_waitcnt vmcnt(1)
	ds_read_b128 v[132:135], v174 offset:192
	s_waitcnt vmcnt(0)
	ds_read_b128 v[136:139], v174 offset:160
	ds_read_b128 v[140:143], v174 offset:128
	s_waitcnt lgkmcnt(3)
	v_pk_mul_f32 v[46:47], v[46:47], v[130:131]
	s_waitcnt lgkmcnt(2)
	v_pk_mul_f32 v[42:43], v[42:43], v[134:135]
	s_waitcnt lgkmcnt(1)
	v_pk_mul_f32 v[38:39], v[38:39], v[138:139]
	s_waitcnt lgkmcnt(0)
	v_pk_mul_f32 v[34:35], v[34:35], v[142:143]
	v_pk_mul_f32 v[44:45], v[44:45], v[128:129]
	v_pk_mul_f32 v[40:41], v[40:41], v[132:133]
	v_pk_mul_f32 v[36:37], v[36:37], v[136:137]
	v_pk_mul_f32 v[32:33], v[32:33], v[140:141]
	v_pk_mul_f32 v[62:63], v[62:63], v[130:131]
	v_pk_mul_f32 v[58:59], v[58:59], v[134:135]
	v_pk_mul_f32 v[54:55], v[54:55], v[138:139]
	v_pk_mul_f32 v[50:51], v[50:51], v[142:143]
	v_pk_mul_f32 v[60:61], v[60:61], v[128:129]
	v_pk_mul_f32 v[56:57], v[56:57], v[132:133]
	v_pk_mul_f32 v[52:53], v[52:53], v[136:137]
	v_pk_mul_f32 v[48:49], v[48:49], v[140:141]
	v_pk_mul_f32 v[30:31], v[30:31], v[130:131]
	v_pk_mul_f32 v[26:27], v[26:27], v[134:135]
	v_pk_mul_f32 v[22:23], v[22:23], v[138:139]
	v_pk_mul_f32 v[18:19], v[18:19], v[142:143]
	v_pk_mul_f32 v[28:29], v[28:29], v[128:129]
	v_pk_mul_f32 v[24:25], v[24:25], v[132:133]
	v_pk_mul_f32 v[20:21], v[20:21], v[136:137]
	v_pk_mul_f32 v[16:17], v[16:17], v[140:141]
	v_pk_mul_f32 v[14:15], v[14:15], v[130:131]
	v_pk_mul_f32 v[10:11], v[10:11], v[134:135]
	v_pk_mul_f32 v[6:7], v[6:7], v[138:139]
	v_pk_mul_f32 v[2:3], v[2:3], v[142:143]
	v_pk_mul_f32 v[12:13], v[12:13], v[128:129]
	v_pk_mul_f32 v[8:9], v[8:9], v[132:133]
	v_pk_mul_f32 v[4:5], v[4:5], v[136:137]
	v_pk_mul_f32 v[0:1], v[0:1], v[140:141]
.LBB0_221:
	v_add_f32_e32 v64, v186, v187
	v_fmac_f32_e32 v64, v183, v177
	v_add_f32_e32 v177, v216, v217
	s_addk_i32 s74, 0x80
	s_add_i32 s73, s73, 2
	v_fmac_f32_e32 v177, v64, v189
	s_cmp_lt_u32 s73, s71
	v_add_u32_e32 v185, 0xffffff80, v185
	s_waitcnt lgkmcnt(0)
	s_cbranch_scc1 .Lmy_cont
	s_barrier
	s_branch .LBB0_223
.Lmy_cont:
	v_mov_b32_e32 v183, v188
	s_branch .LBB0_205
